# prologue pool-fold loop: batched loads with counted vmcnt, v_fmac accumulation in original order
# speedup vs baseline: 1.0118x; 1.0118x over previous
; __device__ __forceinline__ void p0_poolfold_item(const float* mixw  , const float* scale  , const float* wb2  , bf16* WT  , int item, int lane) {
;     ...
;     for (int d0 = 0; d0 < 256; d0 += 8) {
;         float a[8];
; #pragma unroll
;         for (int j = 0; j < 8; ++j) a[j] = scale[g * 256 + d0 + j] * wb2[(size_t)(g * 256 + d0 + j) * D + n];
; #pragma unroll
;         for (int i = 0; i < 32; ++i)
; #pragma unroll
;             for (int j = 0; j < 8; ++j) acc[i] += mw[(size_t)i * 256 + d0 + j] * a[j];
;     }
.LBB0_25:
	s_add_u32 s30, s85, s28
	s_addc_u32 s31, s86, s29
	global_load_dwordx4 v[68:71], v3, s[30:31]
	global_load_dwordx4 v[64:67], v3, s[30:31] offset:16
	s_mov_b32 s88, 0xffffa000
	s_mov_b32 s89, -1
	v_lshl_add_u64 v[72:73], v[30:31], 0, s[88:89]
	global_load_dword v96, v[72:73], off offset:-4096
	global_load_dword v97, v[72:73], off
	s_mov_b32 s88, 0xffffc000
	s_mov_b32 s89, -1
	v_lshl_add_u64 v[72:73], v[30:31], 0, s[88:89]
	global_load_dword v98, v[72:73], off offset:-4096
	global_load_dword v99, v[72:73], off
	s_mov_b32 s88, 0xffffe000
	s_mov_b32 s89, -1
	v_lshl_add_u64 v[72:73], v[30:31], 0, s[88:89]
	global_load_dword v100, v[72:73], off offset:-4096
	global_load_dword v101, v[72:73], off
	global_load_dword v102, v[30:31], off offset:-4096
	global_load_dword v103, v[30:31], off
	s_add_u32 s30, s4, s28
	s_addc_u32 s31, s84, s29
	global_load_dwordx4 v[112:115], v3, s[30:31]
	global_load_dwordx4 v[116:119], v3, s[30:31] offset:16
	global_load_dwordx4 v[120:123], v3, s[30:31] offset:1024
	global_load_dwordx4 v[124:127], v3, s[30:31] offset:1040
	global_load_dwordx4 v[128:131], v3, s[30:31] offset:2048
	global_load_dwordx4 v[132:135], v3, s[30:31] offset:2064
	global_load_dwordx4 v[136:139], v3, s[30:31] offset:3072
	global_load_dwordx4 v[140:143], v3, s[30:31] offset:3088
	global_load_dwordx4 v[144:147], v56, s[30:31]
	global_load_dwordx4 v[148:151], v56, s[30:31] offset:16
	global_load_dwordx4 v[152:155], v56, s[30:31] offset:1024
	global_load_dwordx4 v[156:159], v56, s[30:31] offset:1040
	global_load_dwordx4 v[160:163], v56, s[30:31] offset:2048
	global_load_dwordx4 v[164:167], v56, s[30:31] offset:2064
	global_load_dwordx4 v[168:171], v56, s[30:31] offset:3072
	global_load_dwordx4 v[172:175], v56, s[30:31] offset:3088
	global_load_dwordx4 v[176:179], v57, s[30:31]
	global_load_dwordx4 v[180:183], v57, s[30:31] offset:16
	global_load_dwordx4 v[184:187], v57, s[30:31] offset:1024
	global_load_dwordx4 v[188:191], v57, s[30:31] offset:1040
	global_load_dwordx4 v[192:195], v57, s[30:31] offset:2048
	global_load_dwordx4 v[196:199], v57, s[30:31] offset:2064
	global_load_dwordx4 v[200:203], v57, s[30:31] offset:3072
	global_load_dwordx4 v[204:207], v57, s[30:31] offset:3088
	global_load_dwordx4 v[208:211], v58, s[30:31]
	global_load_dwordx4 v[212:215], v58, s[30:31] offset:16
	global_load_dwordx4 v[216:219], v58, s[30:31] offset:1024
	global_load_dwordx4 v[220:223], v58, s[30:31] offset:1040
	global_load_dwordx4 v[224:227], v58, s[30:31] offset:2048
	global_load_dwordx4 v[228:231], v58, s[30:31] offset:2064
	global_load_dwordx4 v[232:235], v58, s[30:31] offset:3072
	global_load_dwordx4 v[236:239], v58, s[30:31] offset:3088
	s_waitcnt vmcnt(32)
	v_mul_f32_e32 v104, v68, v96
	v_mul_f32_e32 v105, v69, v97
	v_mul_f32_e32 v106, v70, v98
	v_mul_f32_e32 v107, v71, v99
	v_mul_f32_e32 v108, v64, v100
	v_mul_f32_e32 v109, v65, v101
	v_mul_f32_e32 v110, v66, v102
	v_mul_f32_e32 v111, v67, v103
	s_waitcnt vmcnt(16)
	v_fmac_f32_e32 v28, v112, v104
	v_fmac_f32_e32 v28, v113, v105
	v_fmac_f32_e32 v28, v114, v106
	v_fmac_f32_e32 v28, v115, v107
	v_fmac_f32_e32 v28, v116, v108
	v_fmac_f32_e32 v28, v117, v109
	v_fmac_f32_e32 v28, v118, v110
	v_fmac_f32_e32 v28, v119, v111
	v_fmac_f32_e32 v36, v120, v104
	v_fmac_f32_e32 v36, v121, v105
	v_fmac_f32_e32 v36, v122, v106
	v_fmac_f32_e32 v36, v123, v107
	v_fmac_f32_e32 v36, v124, v108
	v_fmac_f32_e32 v36, v125, v109
	v_fmac_f32_e32 v36, v126, v110
	v_fmac_f32_e32 v36, v127, v111
	v_fmac_f32_e32 v29, v128, v104
	v_fmac_f32_e32 v29, v129, v105
	v_fmac_f32_e32 v29, v130, v106
	v_fmac_f32_e32 v29, v131, v107
	v_fmac_f32_e32 v29, v132, v108
	v_fmac_f32_e32 v29, v133, v109
	v_fmac_f32_e32 v29, v134, v110
	v_fmac_f32_e32 v29, v135, v111
	v_fmac_f32_e32 v37, v136, v104
	v_fmac_f32_e32 v37, v137, v105
	v_fmac_f32_e32 v37, v138, v106
	v_fmac_f32_e32 v37, v139, v107
	v_fmac_f32_e32 v37, v140, v108
	v_fmac_f32_e32 v37, v141, v109
	v_fmac_f32_e32 v37, v142, v110
	v_fmac_f32_e32 v37, v143, v111
	v_fmac_f32_e32 v34, v144, v104
	v_fmac_f32_e32 v34, v145, v105
	v_fmac_f32_e32 v34, v146, v106
	v_fmac_f32_e32 v34, v147, v107
	v_fmac_f32_e32 v34, v148, v108
	v_fmac_f32_e32 v34, v149, v109
	v_fmac_f32_e32 v34, v150, v110
	v_fmac_f32_e32 v34, v151, v111
	v_fmac_f32_e32 v38, v152, v104
	v_fmac_f32_e32 v38, v153, v105
	v_fmac_f32_e32 v38, v154, v106
	v_fmac_f32_e32 v38, v155, v107
	v_fmac_f32_e32 v38, v156, v108
	v_fmac_f32_e32 v38, v157, v109
	v_fmac_f32_e32 v38, v158, v110
	v_fmac_f32_e32 v38, v159, v111
	v_fmac_f32_e32 v35, v160, v104
	v_fmac_f32_e32 v35, v161, v105
	v_fmac_f32_e32 v35, v162, v106
	v_fmac_f32_e32 v35, v163, v107
	v_fmac_f32_e32 v35, v164, v108
	v_fmac_f32_e32 v35, v165, v109
	v_fmac_f32_e32 v35, v166, v110
	v_fmac_f32_e32 v35, v167, v111
	v_fmac_f32_e32 v39, v168, v104
	v_fmac_f32_e32 v39, v169, v105
	v_fmac_f32_e32 v39, v170, v106
	v_fmac_f32_e32 v39, v171, v107
	v_fmac_f32_e32 v39, v172, v108
	v_fmac_f32_e32 v39, v173, v109
	v_fmac_f32_e32 v39, v174, v110
	v_fmac_f32_e32 v39, v175, v111
	global_load_dwordx4 v[112:115], v59, s[30:31]
	global_load_dwordx4 v[116:119], v59, s[30:31] offset:16
	global_load_dwordx4 v[120:123], v59, s[30:31] offset:1024
	global_load_dwordx4 v[124:127], v59, s[30:31] offset:1040
	global_load_dwordx4 v[128:131], v59, s[30:31] offset:2048
	global_load_dwordx4 v[132:135], v59, s[30:31] offset:2064
	global_load_dwordx4 v[136:139], v59, s[30:31] offset:3072
	global_load_dwordx4 v[140:143], v59, s[30:31] offset:3088
	global_load_dwordx4 v[144:147], v60, s[30:31]
	global_load_dwordx4 v[148:151], v60, s[30:31] offset:16
	global_load_dwordx4 v[152:155], v60, s[30:31] offset:1024
	global_load_dwordx4 v[156:159], v60, s[30:31] offset:1040
	global_load_dwordx4 v[160:163], v60, s[30:31] offset:2048
	global_load_dwordx4 v[164:167], v60, s[30:31] offset:2064
	global_load_dwordx4 v[168:171], v60, s[30:31] offset:3072
	global_load_dwordx4 v[172:175], v60, s[30:31] offset:3088
	s_waitcnt vmcnt(16)
; __device__ __forceinline__ void p0_poolfold_item(const float* mixw  , const float* scale  , const float* wb2  , bf16* WT  , int item, int lane) {
;     ...
;         for (int i = 0; i < 32; ++i)
; #pragma unroll
;             for (int j = 0; j < 8; ++j) acc[i] += mw[(size_t)i * 256 + d0 + j] * a[j];
	v_fmac_f32_e32 v20, v176, v104
	v_fmac_f32_e32 v20, v177, v105
	v_fmac_f32_e32 v20, v178, v106
	v_fmac_f32_e32 v20, v179, v107
	v_fmac_f32_e32 v20, v180, v108
	v_fmac_f32_e32 v20, v181, v109
	v_fmac_f32_e32 v20, v182, v110
	v_fmac_f32_e32 v20, v183, v111
	v_fmac_f32_e32 v24, v184, v104
	v_fmac_f32_e32 v24, v185, v105
	v_fmac_f32_e32 v24, v186, v106
	v_fmac_f32_e32 v24, v187, v107
	v_fmac_f32_e32 v24, v188, v108
	v_fmac_f32_e32 v24, v189, v109
	v_fmac_f32_e32 v24, v190, v110
	v_fmac_f32_e32 v24, v191, v111
	v_fmac_f32_e32 v21, v192, v104
	v_fmac_f32_e32 v21, v193, v105
	v_fmac_f32_e32 v21, v194, v106
	v_fmac_f32_e32 v21, v195, v107
	v_fmac_f32_e32 v21, v196, v108
	v_fmac_f32_e32 v21, v197, v109
	v_fmac_f32_e32 v21, v198, v110
	v_fmac_f32_e32 v21, v199, v111
	v_fmac_f32_e32 v25, v200, v104
	v_fmac_f32_e32 v25, v201, v105
	v_fmac_f32_e32 v25, v202, v106
	v_fmac_f32_e32 v25, v203, v107
	v_fmac_f32_e32 v25, v204, v108
	v_fmac_f32_e32 v25, v205, v109
	v_fmac_f32_e32 v25, v206, v110
	v_fmac_f32_e32 v25, v207, v111
	v_fmac_f32_e32 v22, v208, v104
	v_fmac_f32_e32 v22, v209, v105
	v_fmac_f32_e32 v22, v210, v106
	v_fmac_f32_e32 v22, v211, v107
	v_fmac_f32_e32 v22, v212, v108
	v_fmac_f32_e32 v22, v213, v109
	v_fmac_f32_e32 v22, v214, v110
	v_fmac_f32_e32 v22, v215, v111
	v_fmac_f32_e32 v26, v216, v104
	v_fmac_f32_e32 v26, v217, v105
	v_fmac_f32_e32 v26, v218, v106
	v_fmac_f32_e32 v26, v219, v107
	v_fmac_f32_e32 v26, v220, v108
	v_fmac_f32_e32 v26, v221, v109
	v_fmac_f32_e32 v26, v222, v110
	v_fmac_f32_e32 v26, v223, v111
	v_fmac_f32_e32 v23, v224, v104
	v_fmac_f32_e32 v23, v225, v105
	v_fmac_f32_e32 v23, v226, v106
	v_fmac_f32_e32 v23, v227, v107
	v_fmac_f32_e32 v23, v228, v108
	v_fmac_f32_e32 v23, v229, v109
	v_fmac_f32_e32 v23, v230, v110
	v_fmac_f32_e32 v23, v231, v111
	v_fmac_f32_e32 v27, v232, v104
	v_fmac_f32_e32 v27, v233, v105
	v_fmac_f32_e32 v27, v234, v106
	v_fmac_f32_e32 v27, v235, v107
	v_fmac_f32_e32 v27, v236, v108
	v_fmac_f32_e32 v27, v237, v109
	v_fmac_f32_e32 v27, v238, v110
	v_fmac_f32_e32 v27, v239, v111
	global_load_dwordx4 v[176:179], v61, s[30:31]
	global_load_dwordx4 v[180:183], v61, s[30:31] offset:16
	global_load_dwordx4 v[184:187], v61, s[30:31] offset:1024
	global_load_dwordx4 v[188:191], v61, s[30:31] offset:1040
	global_load_dwordx4 v[192:195], v61, s[30:31] offset:2048
	global_load_dwordx4 v[196:199], v61, s[30:31] offset:2064
	global_load_dwordx4 v[200:203], v61, s[30:31] offset:3072
	global_load_dwordx4 v[204:207], v61, s[30:31] offset:3088
	global_load_dwordx4 v[208:211], v62, s[30:31]
	global_load_dwordx4 v[212:215], v62, s[30:31] offset:16
	global_load_dwordx4 v[216:219], v62, s[30:31] offset:1024
	global_load_dwordx4 v[220:223], v62, s[30:31] offset:1040
	global_load_dwordx4 v[224:227], v62, s[30:31] offset:2048
	global_load_dwordx4 v[228:231], v62, s[30:31] offset:2064
	global_load_dwordx4 v[232:235], v62, s[30:31] offset:3072
	global_load_dwordx4 v[236:239], v62, s[30:31] offset:3088
	s_waitcnt vmcnt(16)
	v_fmac_f32_e32 v12, v112, v104
	v_fmac_f32_e32 v12, v113, v105
	v_fmac_f32_e32 v12, v114, v106
	v_fmac_f32_e32 v12, v115, v107
	v_fmac_f32_e32 v12, v116, v108
	v_fmac_f32_e32 v12, v117, v109
	v_fmac_f32_e32 v12, v118, v110
	v_fmac_f32_e32 v12, v119, v111
	v_fmac_f32_e32 v16, v120, v104
	v_fmac_f32_e32 v16, v121, v105
	v_fmac_f32_e32 v16, v122, v106
	v_fmac_f32_e32 v16, v123, v107
	v_fmac_f32_e32 v16, v124, v108
	v_fmac_f32_e32 v16, v125, v109
	v_fmac_f32_e32 v16, v126, v110
	v_fmac_f32_e32 v16, v127, v111
	v_fmac_f32_e32 v13, v128, v104
	v_fmac_f32_e32 v13, v129, v105
	v_fmac_f32_e32 v13, v130, v106
	v_fmac_f32_e32 v13, v131, v107
	v_fmac_f32_e32 v13, v132, v108
	v_fmac_f32_e32 v13, v133, v109
	v_fmac_f32_e32 v13, v134, v110
	v_fmac_f32_e32 v13, v135, v111
	v_fmac_f32_e32 v17, v136, v104
	v_fmac_f32_e32 v17, v137, v105
	v_fmac_f32_e32 v17, v138, v106
	v_fmac_f32_e32 v17, v139, v107
	v_fmac_f32_e32 v17, v140, v108
	v_fmac_f32_e32 v17, v141, v109
	v_fmac_f32_e32 v17, v142, v110
	v_fmac_f32_e32 v17, v143, v111
	v_fmac_f32_e32 v14, v144, v104
	v_fmac_f32_e32 v14, v145, v105
	v_fmac_f32_e32 v14, v146, v106
	v_fmac_f32_e32 v14, v147, v107
	v_fmac_f32_e32 v14, v148, v108
	v_fmac_f32_e32 v14, v149, v109
	v_fmac_f32_e32 v14, v150, v110
	v_fmac_f32_e32 v14, v151, v111
	v_fmac_f32_e32 v18, v152, v104
	v_fmac_f32_e32 v18, v153, v105
	v_fmac_f32_e32 v18, v154, v106
	v_fmac_f32_e32 v18, v155, v107
	v_fmac_f32_e32 v18, v156, v108
	v_fmac_f32_e32 v18, v157, v109
	v_fmac_f32_e32 v18, v158, v110
	v_fmac_f32_e32 v18, v159, v111
	v_fmac_f32_e32 v15, v160, v104
	v_fmac_f32_e32 v15, v161, v105
	v_fmac_f32_e32 v15, v162, v106
	v_fmac_f32_e32 v15, v163, v107
	v_fmac_f32_e32 v15, v164, v108
	v_fmac_f32_e32 v15, v165, v109
	v_fmac_f32_e32 v15, v166, v110
	v_fmac_f32_e32 v15, v167, v111
	v_fmac_f32_e32 v19, v168, v104
	v_fmac_f32_e32 v19, v169, v105
	v_fmac_f32_e32 v19, v170, v106
	v_fmac_f32_e32 v19, v171, v107
	v_fmac_f32_e32 v19, v172, v108
	v_fmac_f32_e32 v19, v173, v109
	v_fmac_f32_e32 v19, v174, v110
	v_fmac_f32_e32 v19, v175, v111
	s_waitcnt vmcnt(0)
; #define GAS __attribute__((address_space(1)))
; __device__ __forceinline__ unsigned pk2(float lo, float hi) { return f2bf(lo) | (f2bf(hi) << 16); }
; __device__ __forceinline__ void p0_poolfold_item(const float* mixw  , const float* scale  , const float* wb2  , bf16* WT  , int item, int lane) {
;     ...
;         for (int i = 0; i < 32; ++i)
; #pragma unroll
;             for (int j = 0; j < 8; ++j) acc[i] += mw[(size_t)i * 256 + d0 + j] * a[j];
;     }
;     bf16* dst = WT + (size_t)n * D + g * 256 + c0;
; #pragma unroll
;     for (int i = 0; i < 32; i += 8) { v4u o; o.x = pk2(acc[i], acc[i + 1]); o.y = pk2(acc[i + 2], acc[i + 3]); o.z = pk2(acc[i + 4], acc[i + 5]); o.w = pk2(acc[i + 6], acc[i + 7]); *(GAS v4u*)(dst + i) = o; }
	v_fmac_f32_e32 v6, v176, v104
	v_fmac_f32_e32 v6, v177, v105
	v_fmac_f32_e32 v6, v178, v106
	v_fmac_f32_e32 v6, v179, v107
	v_fmac_f32_e32 v6, v180, v108
	v_fmac_f32_e32 v6, v181, v109
	v_fmac_f32_e32 v6, v182, v110
	v_fmac_f32_e32 v6, v183, v111
	v_fmac_f32_e32 v8, v184, v104
	v_fmac_f32_e32 v8, v185, v105
	v_fmac_f32_e32 v8, v186, v106
	v_fmac_f32_e32 v8, v187, v107
	v_fmac_f32_e32 v8, v188, v108
	v_fmac_f32_e32 v8, v189, v109
	v_fmac_f32_e32 v8, v190, v110
	v_fmac_f32_e32 v8, v191, v111
	v_fmac_f32_e32 v7, v192, v104
	v_fmac_f32_e32 v7, v193, v105
	v_fmac_f32_e32 v7, v194, v106
	v_fmac_f32_e32 v7, v195, v107
	v_fmac_f32_e32 v7, v196, v108
	v_fmac_f32_e32 v7, v197, v109
	v_fmac_f32_e32 v7, v198, v110
	v_fmac_f32_e32 v7, v199, v111
	v_fmac_f32_e32 v9, v200, v104
	v_fmac_f32_e32 v9, v201, v105
	v_fmac_f32_e32 v9, v202, v106
	v_fmac_f32_e32 v9, v203, v107
	v_fmac_f32_e32 v9, v204, v108
	v_fmac_f32_e32 v9, v205, v109
	v_fmac_f32_e32 v9, v206, v110
	v_fmac_f32_e32 v9, v207, v111
	v_fmac_f32_e32 v4, v208, v104
	v_fmac_f32_e32 v4, v209, v105
	v_fmac_f32_e32 v4, v210, v106
	v_fmac_f32_e32 v4, v211, v107
	v_fmac_f32_e32 v4, v212, v108
	v_fmac_f32_e32 v4, v213, v109
	v_fmac_f32_e32 v4, v214, v110
	v_fmac_f32_e32 v4, v215, v111
	v_fmac_f32_e32 v10, v216, v104
	v_fmac_f32_e32 v10, v217, v105
	v_fmac_f32_e32 v10, v218, v106
	v_fmac_f32_e32 v10, v219, v107
	v_fmac_f32_e32 v10, v220, v108
	v_fmac_f32_e32 v10, v221, v109
	v_fmac_f32_e32 v10, v222, v110
	v_fmac_f32_e32 v10, v223, v111
	v_fmac_f32_e32 v5, v224, v104
	v_fmac_f32_e32 v5, v225, v105
	v_fmac_f32_e32 v5, v226, v106
	v_fmac_f32_e32 v5, v227, v107
	v_fmac_f32_e32 v5, v228, v108
	v_fmac_f32_e32 v5, v229, v109
	v_fmac_f32_e32 v5, v230, v110
	v_fmac_f32_e32 v5, v231, v111
	v_fmac_f32_e32 v11, v232, v104
	v_fmac_f32_e32 v11, v233, v105
	v_fmac_f32_e32 v11, v234, v106
	v_fmac_f32_e32 v11, v235, v107
	v_fmac_f32_e32 v11, v236, v108
	v_fmac_f32_e32 v11, v237, v109
	v_fmac_f32_e32 v11, v238, v110
	v_fmac_f32_e32 v11, v239, v111
	s_mov_b64 s[30:31], 0x8000
	v_lshl_add_u64 v[30:31], v[30:31], 0, s[30:31]
	s_add_i32 s87, s87, 8
	s_add_u32 s28, s28, 32
	s_addc_u32 s29, s29, 0
	s_cmpk_lt_u32 s87, 0xf8
	s_cbranch_scc1 .LBB0_25
	s_add_i32 s28, s77, 0xffffc500
	s_lshl_b32 s4, s28, 6
	s_and_b32 s4, s4, 0x3c0
	v_add_u32_e32 v30, s4, v32
	s_lshl_b32 s4, s28, 1
	s_and_b32 s4, s4, 0xffffff00
	v_ashrrev_i32_e32 v31, 31, v30
	s_add_u32 s26, s26, s78
	s_addc_u32 s27, s27, 0
	v_lshlrev_b64 v[30:31], 11, v[30:31]
	v_lshl_add_u64 v[30:31], s[26:27], 0, v[30:31]
	v_lshl_add_u64 v[30:31], s[4:5], 1, v[30:31]
	s_lshl_b32 s4, s28, 2
	s_and_b32 s4, s4, 0x1c0
	v_bfe_u32 v2, v39, 16, 1
	v_lshl_add_u64 v[64:65], v[30:31], 0, s[4:5]
	v_bfe_u32 v30, v38, 16, 1
	v_bfe_u32 v31, v37, 16, 1
	v_bfe_u32 v40, v36, 16, 1
	v_add3_u32 v2, v39, v2, s38
	v_bfe_u32 v39, v34, 16, 1
	v_add3_u32 v36, v36, v40, s38
	v_add3_u32 v37, v37, v31, s38
	v_add3_u32 v30, v38, v30, s38
	v_bfe_u32 v31, v28, 16, 1
	v_bfe_u32 v38, v29, 16, 1
	v_bfe_u32 v40, v35, 16, 1
	v_add3_u32 v34, v34, v39, s38
	v_add3_u32 v35, v35, v40, s38
	v_add3_u32 v29, v29, v38, s38
	v_add3_u32 v28, v28, v31, s38
	v_lshrrev_b32_e32 v34, 16, v34
	s_mov_b32 s4, 0x99c40000
	v_lshrrev_b32_e32 v28, 16, v28
	v_lshrrev_b32_e32 v29, 16, v29
	v_lshrrev_b32_e32 v31, 16, v35
	v_and_or_b32 v30, v30, s39, v34
	v_add_co_u32_e32 v34, vcc, s4, v64
	v_and_or_b32 v31, v2, s39, v31
	v_and_or_b32 v29, v37, s39, v29
	v_and_or_b32 v28, v36, s39, v28
	v_addc_co_u32_e32 v35, vcc, 0, v65, vcc
	global_store_dwordx4 v[34:35], v[28:31], off
	v_bfe_u32 v2, v27, 16, 1
	v_add3_u32 v2, v27, v2, s38
	v_bfe_u32 v28, v26, 16, 1
	v_bfe_u32 v29, v25, 16, 1
	v_bfe_u32 v30, v24, 16, 1
	v_add3_u32 v24, v24, v30, s38
	v_add3_u32 v25, v25, v29, s38
	v_add3_u32 v26, v26, v28, s38
	v_bfe_u32 v27, v20, 16, 1
	v_bfe_u32 v28, v21, 16, 1
	v_bfe_u32 v29, v22, 16, 1
	v_bfe_u32 v30, v23, 16, 1
	v_add3_u32 v23, v23, v30, s38
	v_add3_u32 v22, v22, v29, s38
	v_add3_u32 v21, v21, v28, s38
	v_add3_u32 v20, v20, v27, s38
	s_mov_b64 s[26:27], 0x99c40000
	v_lshrrev_b32_e32 v20, 16, v20
	v_lshrrev_b32_e32 v21, 16, v21
	v_lshrrev_b32_e32 v22, 16, v22
	v_lshrrev_b32_e32 v23, 16, v23
	v_lshl_add_u64 v[66:67], v[64:65], 0, s[26:27]
	v_and_or_b32 v23, v2, s39, v23
	v_and_or_b32 v22, v26, s39, v22
	v_and_or_b32 v21, v25, s39, v21
	v_and_or_b32 v20, v24, s39, v20
	global_store_dwordx4 v[66:67], v[20:23], off offset:16
	v_bfe_u32 v2, v19, 16, 1
	v_add3_u32 v2, v19, v2, s38
	v_bfe_u32 v20, v18, 16, 1
	v_bfe_u32 v21, v17, 16, 1
	v_bfe_u32 v22, v16, 16, 1
	v_add3_u32 v16, v16, v22, s38
	v_add3_u32 v17, v17, v21, s38
	v_add3_u32 v18, v18, v20, s38
	v_bfe_u32 v19, v12, 16, 1
	v_bfe_u32 v20, v13, 16, 1
	v_bfe_u32 v21, v14, 16, 1
	v_bfe_u32 v22, v15, 16, 1
	v_add3_u32 v15, v15, v22, s38
	v_add3_u32 v14, v14, v21, s38
	v_add3_u32 v13, v13, v20, s38
	v_add3_u32 v12, v12, v19, s38
	v_lshrrev_b32_e32 v12, 16, v12
	v_lshrrev_b32_e32 v13, 16, v13
	v_lshrrev_b32_e32 v14, 16, v14
	v_lshrrev_b32_e32 v15, 16, v15
	v_and_or_b32 v15, v2, s39, v15
	v_and_or_b32 v14, v18, s39, v14
	v_and_or_b32 v13, v17, s39, v13
	v_and_or_b32 v12, v16, s39, v12
	global_store_dwordx4 v[66:67], v[12:15], off offset:32
	v_bfe_u32 v2, v11, 16, 1
	v_add3_u32 v2, v11, v2, s38
	v_bfe_u32 v12, v10, 16, 1
	v_bfe_u32 v13, v9, 16, 1
	v_bfe_u32 v14, v8, 16, 1
	v_add3_u32 v8, v8, v14, s38
	v_add3_u32 v9, v9, v13, s38
	v_add3_u32 v10, v10, v12, s38
	v_bfe_u32 v11, v6, 16, 1
	v_bfe_u32 v12, v7, 16, 1
	v_bfe_u32 v13, v4, 16, 1
	v_bfe_u32 v14, v5, 16, 1
	v_add3_u32 v5, v5, v14, s38
	v_add3_u32 v4, v4, v13, s38
	v_add3_u32 v7, v7, v12, s38
	v_add3_u32 v6, v6, v11, s38
	v_lshrrev_b32_e32 v11, 16, v6
	v_lshrrev_b32_e32 v12, 16, v7
	v_lshrrev_b32_e32 v4, 16, v4
	v_lshrrev_b32_e32 v5, 16, v5
	v_and_or_b32 v7, v2, s39, v5
	v_and_or_b32 v6, v10, s39, v4
	v_and_or_b32 v5, v9, s39, v12
	v_and_or_b32 v4, v8, s39, v11
	global_store_dwordx4 v[66:67], v[4:7], off offset:48
	s_mov_b64 s[26:27], 0
